# v47 plus non-temporal (nt) policy on the read-once gate and residual loads of the P4/P5 GEMM epilogues, so they stop evicting A/B tiles from L2
# baseline (speedup 1.0000x reference)
; DI unsigned pk2(float lo, float hi) { f32x2 v = {lo, hi}; bf16v2 r = __builtin_convertvector(v, bf16v2); return __builtin_bit_cast(unsigned, r); }
; DI float bflo(unsigned w) { return __uint_as_float(w << 16); }
; DI float bfhi(unsigned w) { return __uint_as_float(w & 0xffff0000u); }
;     DI void operator()(const f32x4 (&acc)[2][2][4][2], const pg8::Unit& u, int wr, int wc, int fr, int fq) const {
;         const int row0 = u.pm * 256 + wr * 64 + fr, col0 = u.pn * 256 + wc * 32 + 8 * fq;
; #pragma unroll
;         for (int ai = 0; ai < 2; ++ai)
; #pragma unroll
;             for (int m = 0; m < 4; ++m) { const size_t off = (size_t)(row0 + ai * 128 + m * 16) * D + col0;
; #pragma unroll
;                 for (int bj = 0; bj < 2; ++bj) { const f32x4 v0 = acc[ai][bj][m][0], v1 = acc[ai][bj][m][1];
;                     const u32x4 gw = *(const u32x4*)(SMA + off + bj * 128);
;                     u32x4 w; w.x = pk2(v0[0] * bflo(gw.x), v0[1] * bfhi(gw.x)); w.y = pk2(v0[2] * bflo(gw.y), v0[3] * bfhi(gw.y)); w.z = pk2(v1[0] * bflo(gw.z), v1[1] * bfhi(gw.z)); w.w = pk2(v1[2] * bflo(gw.w), v1[3] * bfhi(gw.w));
;                     *(u32x4*)(MG + off + bj * 128) = w; }
;                 asm volatile("" ::: "memory"); }
;     }
.LBB0_110:
	s_cmp_lg_u32 s33, 0
	s_cselect_b64 s[20:21], -1, 0
	v_lshl_add_u32 v160, s36, 8, v166
	v_lshl_or_b32 v162, s35, 8, v168
	v_ashrrev_i32_e32 v161, 31, v160
	v_ashrrev_i32_e32 v163, 31, v162
	s_and_b64 vcc, exec, s[20:21]
	v_or_b32_e32 v134, 16, v160
	v_or_b32_e32 v132, 32, v160
	v_or_b32_e32 v50, 48, v160
	s_cbranch_vccz .LBB0_118
	v_lshlrev_b32_e32 v164, 11, v160
	v_lshl_add_u32 v164, v162, 1, v164
	s_mov_b64 s[2:3], s[78:79]
	global_load_dwordx4 v[178:181], v164, s[2:3] nt
	global_load_dwordx4 v[182:185], v164, s[2:3] offset:256 nt
	s_add_u32 s2, s2, 0x8000
	s_addc_u32 s3, s3, 0
	global_load_dwordx4 v[186:189], v164, s[2:3] nt
	global_load_dwordx4 v[190:193], v164, s[2:3] offset:256 nt
	s_add_u32 s2, s2, 0x8000
	s_addc_u32 s3, s3, 0
	global_load_dwordx4 v[194:197], v164, s[2:3] nt
	global_load_dwordx4 v[198:201], v164, s[2:3] offset:256 nt
	s_add_u32 s2, s2, 0x8000
	s_addc_u32 s3, s3, 0
	global_load_dwordx4 v[202:205], v164, s[2:3] nt
	global_load_dwordx4 v[206:209], v164, s[2:3] offset:256 nt
	s_add_u32 s2, s2, 0x28000
	s_addc_u32 s3, s3, 0
	global_load_dwordx4 v[210:213], v164, s[2:3] nt
	global_load_dwordx4 v[214:217], v164, s[2:3] offset:256 nt
	s_add_u32 s2, s2, 0x8000
	s_addc_u32 s3, s3, 0
	global_load_dwordx4 v[218:221], v164, s[2:3] nt
	global_load_dwordx4 v[222:225], v164, s[2:3] offset:256 nt
	s_add_u32 s2, s2, 0x8000
	s_addc_u32 s3, s3, 0
	global_load_dwordx4 v[226:229], v164, s[2:3] nt
	global_load_dwordx4 v[230:233], v164, s[2:3] offset:256 nt
	s_add_u32 s2, s2, 0x8000
	s_addc_u32 s3, s3, 0
	global_load_dwordx4 v[132:135], v164, s[2:3] nt
	global_load_dwordx4 v[160:163], v164, s[2:3] offset:256 nt
	s_mov_b64 s[2:3], s[68:69]
	s_waitcnt vmcnt(15)
	v_lshlrev_b32_e32 v170, 16, v178
	v_and_b32_e32 v171, 0xffff0000, v178
	v_lshlrev_b32_e32 v50, 16, v179
	v_and_b32_e32 v51, 0xffff0000, v179
	v_pk_mul_f32 v[170:171], v[128:129], v[170:171]
	v_pk_mul_f32 v[50:51], v[130:131], v[50:51]
	s_nop 0
	v_cvt_pk_bf16_f32 v178, v170, v171
	v_cvt_pk_bf16_f32 v179, v50, v51
	v_lshlrev_b32_e32 v170, 16, v180
	v_and_b32_e32 v171, 0xffff0000, v180
	v_lshlrev_b32_e32 v50, 16, v181
	v_and_b32_e32 v51, 0xffff0000, v181
	v_pk_mul_f32 v[170:171], v[124:125], v[170:171]
	v_pk_mul_f32 v[50:51], v[126:127], v[50:51]
	s_nop 0
	v_cvt_pk_bf16_f32 v180, v170, v171
	v_cvt_pk_bf16_f32 v181, v50, v51
	global_store_dwordx4 v164, v[178:181], s[2:3]
	s_waitcnt vmcnt(15)
	v_lshlrev_b32_e32 v170, 16, v182
	v_and_b32_e32 v171, 0xffff0000, v182
	v_lshlrev_b32_e32 v50, 16, v183
	v_and_b32_e32 v51, 0xffff0000, v183
	v_pk_mul_f32 v[170:171], v[96:97], v[170:171]
	v_pk_mul_f32 v[50:51], v[98:99], v[50:51]
	s_nop 0
	v_cvt_pk_bf16_f32 v182, v170, v171
	v_cvt_pk_bf16_f32 v183, v50, v51
	v_lshlrev_b32_e32 v170, 16, v184
	v_and_b32_e32 v171, 0xffff0000, v184
	v_lshlrev_b32_e32 v50, 16, v185
	v_and_b32_e32 v51, 0xffff0000, v185
	v_pk_mul_f32 v[170:171], v[92:93], v[170:171]
	v_pk_mul_f32 v[50:51], v[94:95], v[50:51]
	s_nop 0
	v_cvt_pk_bf16_f32 v184, v170, v171
	v_cvt_pk_bf16_f32 v185, v50, v51
	global_store_dwordx4 v164, v[182:185], s[2:3] offset:256
	s_add_u32 s2, s2, 0x8000
	s_addc_u32 s3, s3, 0
	s_waitcnt vmcnt(15)
	v_lshlrev_b32_e32 v170, 16, v186
	v_and_b32_e32 v171, 0xffff0000, v186
	v_lshlrev_b32_e32 v50, 16, v187
	v_and_b32_e32 v51, 0xffff0000, v187
	v_pk_mul_f32 v[170:171], v[120:121], v[170:171]
	v_pk_mul_f32 v[50:51], v[122:123], v[50:51]
	s_nop 0
	v_cvt_pk_bf16_f32 v186, v170, v171
	v_cvt_pk_bf16_f32 v187, v50, v51
	v_lshlrev_b32_e32 v170, 16, v188
	v_and_b32_e32 v171, 0xffff0000, v188
	v_lshlrev_b32_e32 v50, 16, v189
	v_and_b32_e32 v51, 0xffff0000, v189
	v_pk_mul_f32 v[170:171], v[116:117], v[170:171]
	v_pk_mul_f32 v[50:51], v[118:119], v[50:51]
	s_nop 0
	v_cvt_pk_bf16_f32 v188, v170, v171
	v_cvt_pk_bf16_f32 v189, v50, v51
	global_store_dwordx4 v164, v[186:189], s[2:3]
	s_waitcnt vmcnt(15)
	v_lshlrev_b32_e32 v170, 16, v190
	v_and_b32_e32 v171, 0xffff0000, v190
	v_lshlrev_b32_e32 v50, 16, v191
	v_and_b32_e32 v51, 0xffff0000, v191
	v_pk_mul_f32 v[170:171], v[88:89], v[170:171]
	v_pk_mul_f32 v[50:51], v[90:91], v[50:51]
	s_nop 0
	v_cvt_pk_bf16_f32 v190, v170, v171
	v_cvt_pk_bf16_f32 v191, v50, v51
	v_lshlrev_b32_e32 v170, 16, v192
	v_and_b32_e32 v171, 0xffff0000, v192
	v_lshlrev_b32_e32 v50, 16, v193
	v_and_b32_e32 v51, 0xffff0000, v193
	v_pk_mul_f32 v[170:171], v[84:85], v[170:171]
	v_pk_mul_f32 v[50:51], v[86:87], v[50:51]
	s_nop 0
	v_cvt_pk_bf16_f32 v192, v170, v171
	v_cvt_pk_bf16_f32 v193, v50, v51
	global_store_dwordx4 v164, v[190:193], s[2:3] offset:256
	s_add_u32 s2, s2, 0x8000
	s_addc_u32 s3, s3, 0
	s_waitcnt vmcnt(15)
	v_lshlrev_b32_e32 v170, 16, v194
	v_and_b32_e32 v171, 0xffff0000, v194
	v_lshlrev_b32_e32 v50, 16, v195
	v_and_b32_e32 v51, 0xffff0000, v195
	v_pk_mul_f32 v[170:171], v[112:113], v[170:171]
	v_pk_mul_f32 v[50:51], v[114:115], v[50:51]
	s_nop 0
	v_cvt_pk_bf16_f32 v194, v170, v171
	v_cvt_pk_bf16_f32 v195, v50, v51
	v_lshlrev_b32_e32 v170, 16, v196
	v_and_b32_e32 v171, 0xffff0000, v196
	v_lshlrev_b32_e32 v50, 16, v197
	v_and_b32_e32 v51, 0xffff0000, v197
	v_pk_mul_f32 v[170:171], v[108:109], v[170:171]
	v_pk_mul_f32 v[50:51], v[110:111], v[50:51]
	s_nop 0
	v_cvt_pk_bf16_f32 v196, v170, v171
	v_cvt_pk_bf16_f32 v197, v50, v51
	global_store_dwordx4 v164, v[194:197], s[2:3]
	s_waitcnt vmcnt(15)
; DI unsigned pk2(float lo, float hi) { f32x2 v = {lo, hi}; bf16v2 r = __builtin_convertvector(v, bf16v2); return __builtin_bit_cast(unsigned, r); }
; DI float bflo(unsigned w) { return __uint_as_float(w << 16); }
; DI float bfhi(unsigned w) { return __uint_as_float(w & 0xffff0000u); }
;     DI void operator()(const f32x4 (&acc)[2][2][4][2], const pg8::Unit& u, int wr, int wc, int fr, int fq) const {
;         const int row0 = u.pm * 256 + wr * 64 + fr, col0 = u.pn * 256 + wc * 32 + 8 * fq;
; #pragma unroll
;         for (int ai = 0; ai < 2; ++ai)
; #pragma unroll
;             for (int m = 0; m < 4; ++m) { const size_t off = (size_t)(row0 + ai * 128 + m * 16) * D + col0;
; #pragma unroll
;                 for (int bj = 0; bj < 2; ++bj) { const f32x4 v0 = acc[ai][bj][m][0], v1 = acc[ai][bj][m][1];
;                     const u32x4 gw = *(const u32x4*)(SMA + off + bj * 128);
;                     u32x4 w; w.x = pk2(v0[0] * bflo(gw.x), v0[1] * bfhi(gw.x)); w.y = pk2(v0[2] * bflo(gw.y), v0[3] * bfhi(gw.y)); w.z = pk2(v1[0] * bflo(gw.z), v1[1] * bfhi(gw.z)); w.w = pk2(v1[2] * bflo(gw.w), v1[3] * bfhi(gw.w));
;                     *(u32x4*)(MG + off + bj * 128) = w; }
;                 asm volatile("" ::: "memory"); }
;     }
	v_lshlrev_b32_e32 v170, 16, v198
	v_and_b32_e32 v171, 0xffff0000, v198
	v_lshlrev_b32_e32 v50, 16, v199
	v_and_b32_e32 v51, 0xffff0000, v199
	v_pk_mul_f32 v[170:171], v[80:81], v[170:171]
	v_pk_mul_f32 v[50:51], v[82:83], v[50:51]
	s_nop 0
	v_cvt_pk_bf16_f32 v198, v170, v171
	v_cvt_pk_bf16_f32 v199, v50, v51
	v_lshlrev_b32_e32 v170, 16, v200
	v_and_b32_e32 v171, 0xffff0000, v200
	v_lshlrev_b32_e32 v50, 16, v201
	v_and_b32_e32 v51, 0xffff0000, v201
	v_pk_mul_f32 v[170:171], v[76:77], v[170:171]
	v_pk_mul_f32 v[50:51], v[78:79], v[50:51]
	s_nop 0
	v_cvt_pk_bf16_f32 v200, v170, v171
	v_cvt_pk_bf16_f32 v201, v50, v51
	global_store_dwordx4 v164, v[198:201], s[2:3] offset:256
	s_add_u32 s2, s2, 0x8000
	s_addc_u32 s3, s3, 0
	s_waitcnt vmcnt(15)
	v_lshlrev_b32_e32 v170, 16, v202
	v_and_b32_e32 v171, 0xffff0000, v202
	v_lshlrev_b32_e32 v50, 16, v203
	v_and_b32_e32 v51, 0xffff0000, v203
	v_pk_mul_f32 v[170:171], v[104:105], v[170:171]
	v_pk_mul_f32 v[50:51], v[106:107], v[50:51]
	s_nop 0
	v_cvt_pk_bf16_f32 v202, v170, v171
	v_cvt_pk_bf16_f32 v203, v50, v51
	v_lshlrev_b32_e32 v170, 16, v204
	v_and_b32_e32 v171, 0xffff0000, v204
	v_lshlrev_b32_e32 v50, 16, v205
	v_and_b32_e32 v51, 0xffff0000, v205
	v_pk_mul_f32 v[170:171], v[100:101], v[170:171]
	v_pk_mul_f32 v[50:51], v[102:103], v[50:51]
	s_nop 0
	v_cvt_pk_bf16_f32 v204, v170, v171
	v_cvt_pk_bf16_f32 v205, v50, v51
	global_store_dwordx4 v164, v[202:205], s[2:3]
	s_waitcnt vmcnt(15)
	v_lshlrev_b32_e32 v170, 16, v206
	v_and_b32_e32 v171, 0xffff0000, v206
	v_lshlrev_b32_e32 v50, 16, v207
	v_and_b32_e32 v51, 0xffff0000, v207
	v_pk_mul_f32 v[170:171], v[72:73], v[170:171]
	v_pk_mul_f32 v[50:51], v[74:75], v[50:51]
	s_nop 0
	v_cvt_pk_bf16_f32 v206, v170, v171
	v_cvt_pk_bf16_f32 v207, v50, v51
	v_lshlrev_b32_e32 v170, 16, v208
	v_and_b32_e32 v171, 0xffff0000, v208
	v_lshlrev_b32_e32 v50, 16, v209
	v_and_b32_e32 v51, 0xffff0000, v209
	v_pk_mul_f32 v[170:171], v[68:69], v[170:171]
	v_pk_mul_f32 v[50:51], v[70:71], v[50:51]
	s_nop 0
	v_cvt_pk_bf16_f32 v208, v170, v171
	v_cvt_pk_bf16_f32 v209, v50, v51
	global_store_dwordx4 v164, v[206:209], s[2:3] offset:256
	s_add_u32 s2, s2, 0x28000
	s_addc_u32 s3, s3, 0
	s_waitcnt vmcnt(15)
	v_lshlrev_b32_e32 v170, 16, v210
	v_and_b32_e32 v171, 0xffff0000, v210
	v_lshlrev_b32_e32 v50, 16, v211
	v_and_b32_e32 v51, 0xffff0000, v211
	v_pk_mul_f32 v[170:171], v[64:65], v[170:171]
	v_pk_mul_f32 v[50:51], v[66:67], v[50:51]
	s_nop 0
	v_cvt_pk_bf16_f32 v210, v170, v171
	v_cvt_pk_bf16_f32 v211, v50, v51
	v_lshlrev_b32_e32 v170, 16, v212
	v_and_b32_e32 v171, 0xffff0000, v212
	v_lshlrev_b32_e32 v50, 16, v213
	v_and_b32_e32 v51, 0xffff0000, v213
	v_pk_mul_f32 v[170:171], v[60:61], v[170:171]
	v_pk_mul_f32 v[50:51], v[62:63], v[50:51]
	s_nop 0
	v_cvt_pk_bf16_f32 v212, v170, v171
	v_cvt_pk_bf16_f32 v213, v50, v51
	global_store_dwordx4 v164, v[210:213], s[2:3]
	s_waitcnt vmcnt(15)
	v_lshlrev_b32_e32 v170, 16, v214
	v_and_b32_e32 v171, 0xffff0000, v214
	v_lshlrev_b32_e32 v50, 16, v215
	v_and_b32_e32 v51, 0xffff0000, v215
	v_pk_mul_f32 v[170:171], v[28:29], v[170:171]
	v_pk_mul_f32 v[50:51], v[30:31], v[50:51]
	s_nop 0
	v_cvt_pk_bf16_f32 v214, v170, v171
	v_cvt_pk_bf16_f32 v215, v50, v51
	v_lshlrev_b32_e32 v170, 16, v216
	v_and_b32_e32 v171, 0xffff0000, v216
	v_lshlrev_b32_e32 v50, 16, v217
	v_and_b32_e32 v51, 0xffff0000, v217
	v_pk_mul_f32 v[170:171], v[24:25], v[170:171]
	v_pk_mul_f32 v[50:51], v[26:27], v[50:51]
	s_nop 0
	v_cvt_pk_bf16_f32 v216, v170, v171
	v_cvt_pk_bf16_f32 v217, v50, v51
	global_store_dwordx4 v164, v[214:217], s[2:3] offset:256
	s_add_u32 s2, s2, 0x8000
	s_addc_u32 s3, s3, 0
	s_waitcnt vmcnt(15)
	v_lshlrev_b32_e32 v170, 16, v218
	v_and_b32_e32 v171, 0xffff0000, v218
	v_lshlrev_b32_e32 v50, 16, v219
	v_and_b32_e32 v51, 0xffff0000, v219
	v_pk_mul_f32 v[170:171], v[56:57], v[170:171]
	v_pk_mul_f32 v[50:51], v[58:59], v[50:51]
	s_nop 0
	v_cvt_pk_bf16_f32 v218, v170, v171
	v_cvt_pk_bf16_f32 v219, v50, v51
	v_lshlrev_b32_e32 v170, 16, v220
	v_and_b32_e32 v171, 0xffff0000, v220
	v_lshlrev_b32_e32 v50, 16, v221
	v_and_b32_e32 v51, 0xffff0000, v221
	v_pk_mul_f32 v[170:171], v[52:53], v[170:171]
	v_pk_mul_f32 v[50:51], v[54:55], v[50:51]
	s_nop 0
	v_cvt_pk_bf16_f32 v220, v170, v171
	v_cvt_pk_bf16_f32 v221, v50, v51
	global_store_dwordx4 v164, v[218:221], s[2:3]
	s_waitcnt vmcnt(15)
	v_lshlrev_b32_e32 v170, 16, v222
	v_and_b32_e32 v171, 0xffff0000, v222
	v_lshlrev_b32_e32 v50, 16, v223
	v_and_b32_e32 v51, 0xffff0000, v223
	v_pk_mul_f32 v[170:171], v[20:21], v[170:171]
	v_pk_mul_f32 v[50:51], v[22:23], v[50:51]
	s_nop 0
	v_cvt_pk_bf16_f32 v222, v170, v171
	v_cvt_pk_bf16_f32 v223, v50, v51
	v_lshlrev_b32_e32 v170, 16, v224
	v_and_b32_e32 v171, 0xffff0000, v224
	v_lshlrev_b32_e32 v50, 16, v225
	v_and_b32_e32 v51, 0xffff0000, v225
	v_pk_mul_f32 v[170:171], v[16:17], v[170:171]
	v_pk_mul_f32 v[50:51], v[18:19], v[50:51]
	s_nop 0
	v_cvt_pk_bf16_f32 v224, v170, v171
	v_cvt_pk_bf16_f32 v225, v50, v51
	global_store_dwordx4 v164, v[222:225], s[2:3] offset:256
	s_add_u32 s2, s2, 0x8000
	s_addc_u32 s3, s3, 0
	s_waitcnt vmcnt(15)
	v_lshlrev_b32_e32 v170, 16, v226
	v_and_b32_e32 v171, 0xffff0000, v226
	v_lshlrev_b32_e32 v50, 16, v227
	v_and_b32_e32 v51, 0xffff0000, v227
	v_pk_mul_f32 v[170:171], v[44:45], v[170:171]
	v_pk_mul_f32 v[50:51], v[46:47], v[50:51]
	s_nop 0
	v_cvt_pk_bf16_f32 v226, v170, v171
	v_cvt_pk_bf16_f32 v227, v50, v51
	v_lshlrev_b32_e32 v170, 16, v228
	v_and_b32_e32 v171, 0xffff0000, v228
	v_lshlrev_b32_e32 v50, 16, v229
	v_and_b32_e32 v51, 0xffff0000, v229
	v_pk_mul_f32 v[170:171], v[40:41], v[170:171]
	v_pk_mul_f32 v[50:51], v[42:43], v[50:51]
	s_nop 0
	v_cvt_pk_bf16_f32 v228, v170, v171
	v_cvt_pk_bf16_f32 v229, v50, v51
	global_store_dwordx4 v164, v[226:229], s[2:3]
	s_waitcnt vmcnt(15)
; DI unsigned pk2(float lo, float hi) { f32x2 v = {lo, hi}; bf16v2 r = __builtin_convertvector(v, bf16v2); return __builtin_bit_cast(unsigned, r); }
; DI float bflo(unsigned w) { return __uint_as_float(w << 16); }
; DI float bfhi(unsigned w) { return __uint_as_float(w & 0xffff0000u); }
;     DI void mid(f32x4 (&acc)[2][2][4][2], const pg8::Unit& u, int wr, int wc, int fr, int fq) const {
;         const int row0 = u.pm * 256 + wr * 64 + fr, col0 = u.pn * 256 + wc * 32 + 8 * fq;
; #pragma unroll
;         for (int ai = 0; ai < 2; ++ai)
; #pragma unroll
;             for (int m = 0; m < 4; ++m) { const size_t off = (size_t)(row0 + ai * 128 + m * 16) * D + col0;
; #pragma unroll
;                 for (int bj = 0; bj < 2; ++bj) { const u32x4 gw = *(const u32x4*)(RHO + off + bj * 128);
;                     acc[ai][bj][m][0] = acc[ai][bj][m][0] * (f32x4){bflo(gw.x), bfhi(gw.x), bflo(gw.y), bfhi(gw.y)};
;                     acc[ai][bj][m][1] = acc[ai][bj][m][1] * (f32x4){bflo(gw.z), bfhi(gw.z), bflo(gw.w), bfhi(gw.w)}; }
;                 asm volatile("" ::: "memory"); }
;     }
;     DI void operator()(const f32x4 (&acc)[2][2][4][2], const pg8::Unit& u, int wr, int wc, int fr, int fq) const {
;         const int row0 = u.pm * 256 + wr * 64 + fr, col0 = u.pn * 256 + wc * 32 + 8 * fq;
; #pragma unroll
;         for (int ai = 0; ai < 2; ++ai)
; #pragma unroll
;             for (int m = 0; m < 4; ++m) { const size_t off = (size_t)(row0 + ai * 128 + m * 16) * D + col0;
; #pragma unroll
;                 for (int bj = 0; bj < 2; ++bj) { const f32x4 v0 = acc[ai][bj][m][0], v1 = acc[ai][bj][m][1];
;                     const u32x4 gw = *(const u32x4*)(SMA + off + bj * 128);
;                     u32x4 w; w.x = pk2(v0[0] * bflo(gw.x), v0[1] * bfhi(gw.x)); w.y = pk2(v0[2] * bflo(gw.y), v0[3] * bfhi(gw.y)); w.z = pk2(v1[0] * bflo(gw.z), v1[1] * bfhi(gw.z)); w.w = pk2(v1[2] * bflo(gw.w), v1[3] * bfhi(gw.w));
;                     *(u32x4*)(MG + off + bj * 128) = w; }
;                 asm volatile("" ::: "memory"); }
;     }
	v_lshlrev_b32_e32 v170, 16, v230
	v_and_b32_e32 v171, 0xffff0000, v230
	v_lshlrev_b32_e32 v50, 16, v231
	v_and_b32_e32 v51, 0xffff0000, v231
	v_pk_mul_f32 v[170:171], v[12:13], v[170:171]
	v_pk_mul_f32 v[50:51], v[14:15], v[50:51]
	s_nop 0
	v_cvt_pk_bf16_f32 v230, v170, v171
	v_cvt_pk_bf16_f32 v231, v50, v51
	v_lshlrev_b32_e32 v170, 16, v232
	v_and_b32_e32 v171, 0xffff0000, v232
	v_lshlrev_b32_e32 v50, 16, v233
	v_and_b32_e32 v51, 0xffff0000, v233
	v_pk_mul_f32 v[170:171], v[8:9], v[170:171]
	v_pk_mul_f32 v[50:51], v[10:11], v[50:51]
	s_nop 0
	v_cvt_pk_bf16_f32 v232, v170, v171
	v_cvt_pk_bf16_f32 v233, v50, v51
	global_store_dwordx4 v164, v[230:233], s[2:3] offset:256
	s_add_u32 s2, s2, 0x8000
	s_addc_u32 s3, s3, 0
	s_waitcnt vmcnt(15)
	v_lshlrev_b32_e32 v170, 16, v132
	v_and_b32_e32 v171, 0xffff0000, v132
	v_lshlrev_b32_e32 v50, 16, v133
	v_and_b32_e32 v51, 0xffff0000, v133
	v_pk_mul_f32 v[170:171], v[36:37], v[170:171]
	v_pk_mul_f32 v[50:51], v[38:39], v[50:51]
	s_nop 0
	v_cvt_pk_bf16_f32 v132, v170, v171
	v_cvt_pk_bf16_f32 v133, v50, v51
	v_lshlrev_b32_e32 v170, 16, v134
	v_and_b32_e32 v171, 0xffff0000, v134
	v_lshlrev_b32_e32 v50, 16, v135
	v_and_b32_e32 v51, 0xffff0000, v135
	v_pk_mul_f32 v[170:171], v[32:33], v[170:171]
	v_pk_mul_f32 v[50:51], v[34:35], v[50:51]
	s_nop 0
	v_cvt_pk_bf16_f32 v134, v170, v171
	v_cvt_pk_bf16_f32 v135, v50, v51
	global_store_dwordx4 v164, v[132:135], s[2:3]
	s_waitcnt vmcnt(15)
	v_lshlrev_b32_e32 v170, 16, v160
	v_and_b32_e32 v171, 0xffff0000, v160
	v_lshlrev_b32_e32 v50, 16, v161
	v_and_b32_e32 v51, 0xffff0000, v161
	v_pk_mul_f32 v[170:171], v[4:5], v[170:171]
	v_pk_mul_f32 v[50:51], v[6:7], v[50:51]
	s_nop 0
	v_cvt_pk_bf16_f32 v160, v170, v171
	v_cvt_pk_bf16_f32 v161, v50, v51
	v_lshlrev_b32_e32 v170, 16, v162
	v_and_b32_e32 v171, 0xffff0000, v162
	v_lshlrev_b32_e32 v50, 16, v163
	v_and_b32_e32 v51, 0xffff0000, v163
	v_pk_mul_f32 v[170:171], v[0:1], v[170:171]
	v_pk_mul_f32 v[50:51], v[2:3], v[50:51]
	s_nop 0
	v_cvt_pk_bf16_f32 v162, v170, v171
	v_cvt_pk_bf16_f32 v163, v50, v51
	global_store_dwordx4 v164, v[160:163], s[2:3] offset:256
	s_cbranch_execnz .LBB0_113
.LBB0_112:
	v_lshlrev_b32_e32 v164, 11, v160
	v_lshl_add_u32 v164, v162, 1, v164
	s_mov_b64 s[2:3], s[80:81]
	global_load_dwordx4 v[178:181], v164, s[2:3] nt
	global_load_dwordx4 v[182:185], v164, s[2:3] offset:256 nt
	s_add_u32 s2, s2, 0x8000
	s_addc_u32 s3, s3, 0
	global_load_dwordx4 v[186:189], v164, s[2:3] nt
	global_load_dwordx4 v[190:193], v164, s[2:3] offset:256 nt
	s_add_u32 s2, s2, 0x8000
	s_addc_u32 s3, s3, 0
	global_load_dwordx4 v[194:197], v164, s[2:3] nt
	global_load_dwordx4 v[198:201], v164, s[2:3] offset:256 nt
	s_add_u32 s2, s2, 0x8000
	s_addc_u32 s3, s3, 0
	global_load_dwordx4 v[202:205], v164, s[2:3] nt
	global_load_dwordx4 v[206:209], v164, s[2:3] offset:256 nt
	s_add_u32 s2, s2, 0x28000
	s_addc_u32 s3, s3, 0
	global_load_dwordx4 v[210:213], v164, s[2:3] nt
	global_load_dwordx4 v[214:217], v164, s[2:3] offset:256 nt
	s_add_u32 s2, s2, 0x8000
	s_addc_u32 s3, s3, 0
	global_load_dwordx4 v[218:221], v164, s[2:3] nt
	global_load_dwordx4 v[222:225], v164, s[2:3] offset:256 nt
	s_add_u32 s2, s2, 0x8000
	s_addc_u32 s3, s3, 0
	global_load_dwordx4 v[226:229], v164, s[2:3] nt
	global_load_dwordx4 v[230:233], v164, s[2:3] offset:256 nt
	s_add_u32 s2, s2, 0x8000
	s_addc_u32 s3, s3, 0
	global_load_dwordx4 v[132:135], v164, s[2:3] nt
	global_load_dwordx4 v[160:163], v164, s[2:3] offset:256 nt
	s_waitcnt vmcnt(15)
	v_lshlrev_b32_e32 v170, 16, v178
	v_and_b32_e32 v171, 0xffff0000, v178
	v_lshlrev_b32_e32 v50, 16, v179
	v_and_b32_e32 v51, 0xffff0000, v179
	v_pk_mul_f32 v[128:129], v[128:129], v[170:171]
	v_pk_mul_f32 v[130:131], v[130:131], v[50:51]
	v_lshlrev_b32_e32 v170, 16, v180
	v_and_b32_e32 v171, 0xffff0000, v180
	v_lshlrev_b32_e32 v50, 16, v181
	v_and_b32_e32 v51, 0xffff0000, v181
	v_pk_mul_f32 v[124:125], v[124:125], v[170:171]
	v_pk_mul_f32 v[126:127], v[126:127], v[50:51]
	s_waitcnt vmcnt(14)
	v_lshlrev_b32_e32 v170, 16, v182
	v_and_b32_e32 v171, 0xffff0000, v182
	v_lshlrev_b32_e32 v50, 16, v183
	v_and_b32_e32 v51, 0xffff0000, v183
	v_pk_mul_f32 v[96:97], v[96:97], v[170:171]
	v_pk_mul_f32 v[98:99], v[98:99], v[50:51]
	v_lshlrev_b32_e32 v170, 16, v184
	v_and_b32_e32 v171, 0xffff0000, v184
	v_lshlrev_b32_e32 v50, 16, v185
	v_and_b32_e32 v51, 0xffff0000, v185
	v_pk_mul_f32 v[92:93], v[92:93], v[170:171]
	v_pk_mul_f32 v[94:95], v[94:95], v[50:51]
	s_waitcnt vmcnt(13)
	v_lshlrev_b32_e32 v170, 16, v186
	v_and_b32_e32 v171, 0xffff0000, v186
	v_lshlrev_b32_e32 v50, 16, v187
	v_and_b32_e32 v51, 0xffff0000, v187
	v_pk_mul_f32 v[120:121], v[120:121], v[170:171]
	v_pk_mul_f32 v[122:123], v[122:123], v[50:51]
	v_lshlrev_b32_e32 v170, 16, v188
	v_and_b32_e32 v171, 0xffff0000, v188
	v_lshlrev_b32_e32 v50, 16, v189
	v_and_b32_e32 v51, 0xffff0000, v189
	v_pk_mul_f32 v[116:117], v[116:117], v[170:171]
	v_pk_mul_f32 v[118:119], v[118:119], v[50:51]
	s_waitcnt vmcnt(12)
	v_lshlrev_b32_e32 v170, 16, v190
	v_and_b32_e32 v171, 0xffff0000, v190
	v_lshlrev_b32_e32 v50, 16, v191
	v_and_b32_e32 v51, 0xffff0000, v191
	v_pk_mul_f32 v[88:89], v[88:89], v[170:171]
	v_pk_mul_f32 v[90:91], v[90:91], v[50:51]
	v_lshlrev_b32_e32 v170, 16, v192
	v_and_b32_e32 v171, 0xffff0000, v192
	v_lshlrev_b32_e32 v50, 16, v193
	v_and_b32_e32 v51, 0xffff0000, v193
	v_pk_mul_f32 v[84:85], v[84:85], v[170:171]
	v_pk_mul_f32 v[86:87], v[86:87], v[50:51]
	s_waitcnt vmcnt(11)
; DI float bflo(unsigned w) { return __uint_as_float(w << 16); }
; DI float bfhi(unsigned w) { return __uint_as_float(w & 0xffff0000u); }
;     DI void mid(f32x4 (&acc)[2][2][4][2], const pg8::Unit& u, int wr, int wc, int fr, int fq) const {
;         const int row0 = u.pm * 256 + wr * 64 + fr, col0 = u.pn * 256 + wc * 32 + 8 * fq;
; #pragma unroll
;         for (int ai = 0; ai < 2; ++ai)
; #pragma unroll
;             for (int m = 0; m < 4; ++m) { const size_t off = (size_t)(row0 + ai * 128 + m * 16) * D + col0;
; #pragma unroll
;                 for (int bj = 0; bj < 2; ++bj) { const u32x4 gw = *(const u32x4*)(RHO + off + bj * 128);
;                     acc[ai][bj][m][0] = acc[ai][bj][m][0] * (f32x4){bflo(gw.x), bfhi(gw.x), bflo(gw.y), bfhi(gw.y)};
;                     acc[ai][bj][m][1] = acc[ai][bj][m][1] * (f32x4){bflo(gw.z), bfhi(gw.z), bflo(gw.w), bfhi(gw.w)}; }
;                 asm volatile("" ::: "memory"); }
;     }
	v_lshlrev_b32_e32 v170, 16, v194
	v_and_b32_e32 v171, 0xffff0000, v194
	v_lshlrev_b32_e32 v50, 16, v195
	v_and_b32_e32 v51, 0xffff0000, v195
	v_pk_mul_f32 v[112:113], v[112:113], v[170:171]
	v_pk_mul_f32 v[114:115], v[114:115], v[50:51]
	v_lshlrev_b32_e32 v170, 16, v196
	v_and_b32_e32 v171, 0xffff0000, v196
	v_lshlrev_b32_e32 v50, 16, v197
	v_and_b32_e32 v51, 0xffff0000, v197
	v_pk_mul_f32 v[108:109], v[108:109], v[170:171]
	v_pk_mul_f32 v[110:111], v[110:111], v[50:51]
	s_waitcnt vmcnt(10)
	v_lshlrev_b32_e32 v170, 16, v198
	v_and_b32_e32 v171, 0xffff0000, v198
	v_lshlrev_b32_e32 v50, 16, v199
	v_and_b32_e32 v51, 0xffff0000, v199
	v_pk_mul_f32 v[80:81], v[80:81], v[170:171]
	v_pk_mul_f32 v[82:83], v[82:83], v[50:51]
	v_lshlrev_b32_e32 v170, 16, v200
	v_and_b32_e32 v171, 0xffff0000, v200
	v_lshlrev_b32_e32 v50, 16, v201
	v_and_b32_e32 v51, 0xffff0000, v201
	v_pk_mul_f32 v[76:77], v[76:77], v[170:171]
	v_pk_mul_f32 v[78:79], v[78:79], v[50:51]
	s_waitcnt vmcnt(9)
	v_lshlrev_b32_e32 v170, 16, v202
	v_and_b32_e32 v171, 0xffff0000, v202
	v_lshlrev_b32_e32 v50, 16, v203
	v_and_b32_e32 v51, 0xffff0000, v203
	v_pk_mul_f32 v[104:105], v[104:105], v[170:171]
	v_pk_mul_f32 v[106:107], v[106:107], v[50:51]
	v_lshlrev_b32_e32 v170, 16, v204
	v_and_b32_e32 v171, 0xffff0000, v204
	v_lshlrev_b32_e32 v50, 16, v205
	v_and_b32_e32 v51, 0xffff0000, v205
	v_pk_mul_f32 v[100:101], v[100:101], v[170:171]
	v_pk_mul_f32 v[102:103], v[102:103], v[50:51]
	s_waitcnt vmcnt(8)
	v_lshlrev_b32_e32 v170, 16, v206
	v_and_b32_e32 v171, 0xffff0000, v206
	v_lshlrev_b32_e32 v50, 16, v207
	v_and_b32_e32 v51, 0xffff0000, v207
	v_pk_mul_f32 v[72:73], v[72:73], v[170:171]
	v_pk_mul_f32 v[74:75], v[74:75], v[50:51]
	v_lshlrev_b32_e32 v170, 16, v208
	v_and_b32_e32 v171, 0xffff0000, v208
	v_lshlrev_b32_e32 v50, 16, v209
	v_and_b32_e32 v51, 0xffff0000, v209
	v_pk_mul_f32 v[68:69], v[68:69], v[170:171]
	v_pk_mul_f32 v[70:71], v[70:71], v[50:51]
	s_waitcnt vmcnt(7)
	v_lshlrev_b32_e32 v170, 16, v210
	v_and_b32_e32 v171, 0xffff0000, v210
	v_lshlrev_b32_e32 v50, 16, v211
	v_and_b32_e32 v51, 0xffff0000, v211
	v_pk_mul_f32 v[64:65], v[64:65], v[170:171]
	v_pk_mul_f32 v[66:67], v[66:67], v[50:51]
	v_lshlrev_b32_e32 v170, 16, v212
	v_and_b32_e32 v171, 0xffff0000, v212
	v_lshlrev_b32_e32 v50, 16, v213
	v_and_b32_e32 v51, 0xffff0000, v213
	v_pk_mul_f32 v[60:61], v[60:61], v[170:171]
	v_pk_mul_f32 v[62:63], v[62:63], v[50:51]
	s_waitcnt vmcnt(6)
	v_lshlrev_b32_e32 v170, 16, v214
	v_and_b32_e32 v171, 0xffff0000, v214
	v_lshlrev_b32_e32 v50, 16, v215
	v_and_b32_e32 v51, 0xffff0000, v215
	v_pk_mul_f32 v[28:29], v[28:29], v[170:171]
	v_pk_mul_f32 v[30:31], v[30:31], v[50:51]
	v_lshlrev_b32_e32 v170, 16, v216
	v_and_b32_e32 v171, 0xffff0000, v216
	v_lshlrev_b32_e32 v50, 16, v217
	v_and_b32_e32 v51, 0xffff0000, v217
	v_pk_mul_f32 v[24:25], v[24:25], v[170:171]
	v_pk_mul_f32 v[26:27], v[26:27], v[50:51]
	s_waitcnt vmcnt(5)
	v_lshlrev_b32_e32 v170, 16, v218
	v_and_b32_e32 v171, 0xffff0000, v218
	v_lshlrev_b32_e32 v50, 16, v219
	v_and_b32_e32 v51, 0xffff0000, v219
	v_pk_mul_f32 v[56:57], v[56:57], v[170:171]
	v_pk_mul_f32 v[58:59], v[58:59], v[50:51]
	v_lshlrev_b32_e32 v170, 16, v220
	v_and_b32_e32 v171, 0xffff0000, v220
	v_lshlrev_b32_e32 v50, 16, v221
	v_and_b32_e32 v51, 0xffff0000, v221
	v_pk_mul_f32 v[52:53], v[52:53], v[170:171]
	v_pk_mul_f32 v[54:55], v[54:55], v[50:51]
	s_waitcnt vmcnt(4)
	v_lshlrev_b32_e32 v170, 16, v222
	v_and_b32_e32 v171, 0xffff0000, v222
	v_lshlrev_b32_e32 v50, 16, v223
	v_and_b32_e32 v51, 0xffff0000, v223
	v_pk_mul_f32 v[20:21], v[20:21], v[170:171]
	v_pk_mul_f32 v[22:23], v[22:23], v[50:51]
	v_lshlrev_b32_e32 v170, 16, v224
	v_and_b32_e32 v171, 0xffff0000, v224
	v_lshlrev_b32_e32 v50, 16, v225
	v_and_b32_e32 v51, 0xffff0000, v225
	v_pk_mul_f32 v[16:17], v[16:17], v[170:171]
	v_pk_mul_f32 v[18:19], v[18:19], v[50:51]
	s_waitcnt vmcnt(3)
	v_lshlrev_b32_e32 v170, 16, v226
	v_and_b32_e32 v171, 0xffff0000, v226
	v_lshlrev_b32_e32 v50, 16, v227
	v_and_b32_e32 v51, 0xffff0000, v227
	v_pk_mul_f32 v[44:45], v[44:45], v[170:171]
	v_pk_mul_f32 v[46:47], v[46:47], v[50:51]
	v_lshlrev_b32_e32 v170, 16, v228
	v_and_b32_e32 v171, 0xffff0000, v228
	v_lshlrev_b32_e32 v50, 16, v229
	v_and_b32_e32 v51, 0xffff0000, v229
	v_pk_mul_f32 v[40:41], v[40:41], v[170:171]
	v_pk_mul_f32 v[42:43], v[42:43], v[50:51]
	s_waitcnt vmcnt(2)
	v_lshlrev_b32_e32 v170, 16, v230
	v_and_b32_e32 v171, 0xffff0000, v230
	v_lshlrev_b32_e32 v50, 16, v231
	v_and_b32_e32 v51, 0xffff0000, v231
	v_pk_mul_f32 v[12:13], v[12:13], v[170:171]
	v_pk_mul_f32 v[14:15], v[14:15], v[50:51]
	v_lshlrev_b32_e32 v170, 16, v232
	v_and_b32_e32 v171, 0xffff0000, v232
	v_lshlrev_b32_e32 v50, 16, v233
	v_and_b32_e32 v51, 0xffff0000, v233
	v_pk_mul_f32 v[8:9], v[8:9], v[170:171]
	v_pk_mul_f32 v[10:11], v[10:11], v[50:51]
	s_waitcnt vmcnt(1)
	v_lshlrev_b32_e32 v170, 16, v132
	v_and_b32_e32 v171, 0xffff0000, v132
	v_lshlrev_b32_e32 v50, 16, v133
	v_and_b32_e32 v51, 0xffff0000, v133
	v_pk_mul_f32 v[36:37], v[36:37], v[170:171]
	v_pk_mul_f32 v[38:39], v[38:39], v[50:51]
	v_lshlrev_b32_e32 v170, 16, v134
	v_and_b32_e32 v171, 0xffff0000, v134
	v_lshlrev_b32_e32 v50, 16, v135
	v_and_b32_e32 v51, 0xffff0000, v135
	v_pk_mul_f32 v[32:33], v[32:33], v[170:171]
	v_pk_mul_f32 v[34:35], v[34:35], v[50:51]
	s_waitcnt vmcnt(0)
	v_lshlrev_b32_e32 v170, 16, v160
	v_and_b32_e32 v171, 0xffff0000, v160
	v_lshlrev_b32_e32 v50, 16, v161
	v_and_b32_e32 v51, 0xffff0000, v161
	v_pk_mul_f32 v[4:5], v[4:5], v[170:171]
	v_pk_mul_f32 v[6:7], v[6:7], v[50:51]
	v_lshlrev_b32_e32 v170, 16, v162
	v_and_b32_e32 v171, 0xffff0000, v162
	v_lshlrev_b32_e32 v50, 16, v163
	v_and_b32_e32 v51, 0xffff0000, v163
	v_pk_mul_f32 v[0:1], v[0:1], v[170:171]
	v_pk_mul_f32 v[2:3], v[2:3], v[50:51]

;     DI void operator()(const f32x4 (&acc)[2][2][4][2], const pg8::Unit& u, int wr, int wc, int fr, int fq) const {
;         const int row0 = u.pm * 256 + wr * 64 + fr, col0 = u.pn * 256 + wc * 32 + 4 * fq;
; #pragma unroll
;         for (int ai = 0; ai < 2; ++ai)
; #pragma unroll
;             for (int m = 0; m < 4; ++m) { const size_t off = (size_t)(row0 + ai * 128 + m * 16) * D + col0;
; #pragma unroll
;                 for (int bj = 0; bj < 2; ++bj)
; #pragma unroll
;                     for (int n = 0; n < 2; ++n) { const f32x4 xv = *(const f32x4*)(xin + off + bj * 128 + n * 16); *(f32x4*)(out + off + bj * 128 + n * 16) = xv + acc[ai][bj][m][n]; }
;                 asm volatile("" ::: "memory"); }
;     }
.LBB0_223:
	v_lshl_add_u32 v152, s31, 8, v154
	v_lshl_or_b32 v150, s30, 8, v156
	v_lshlrev_b32_e32 v153, 12, v152
	v_lshl_add_u32 v153, v150, 2, v153
	s_andn2_b64 vcc, exec, s[6:7]
	s_mov_b32 s16, s50
	s_mov_b32 s17, s51
	global_load_dwordx4 v[148:151], v153, s[16:17] nt
	global_load_dwordx4 v[158:161], v153, s[16:17] offset:64 nt
	global_load_dwordx4 v[162:165], v153, s[16:17] offset:512 nt
	global_load_dwordx4 v[166:169], v153, s[16:17] offset:576 nt
	s_add_u32 s16, s16, 0x10000
	s_addc_u32 s17, s17, 0
	global_load_dwordx4 v[178:181], v153, s[16:17] nt
	global_load_dwordx4 v[182:185], v153, s[16:17] offset:64 nt
	global_load_dwordx4 v[186:189], v153, s[16:17] offset:512 nt
	global_load_dwordx4 v[190:193], v153, s[16:17] offset:576 nt
	s_add_u32 s16, s16, 0x10000
	s_addc_u32 s17, s17, 0
	global_load_dwordx4 v[194:197], v153, s[16:17] nt
	global_load_dwordx4 v[198:201], v153, s[16:17] offset:64 nt
	global_load_dwordx4 v[202:205], v153, s[16:17] offset:512 nt
	global_load_dwordx4 v[206:209], v153, s[16:17] offset:576 nt
	s_add_u32 s16, s16, 0x10000
	s_addc_u32 s17, s17, 0
	global_load_dwordx4 v[210:213], v153, s[16:17] nt
	global_load_dwordx4 v[214:217], v153, s[16:17] offset:64 nt
	global_load_dwordx4 v[218:221], v153, s[16:17] offset:512 nt
	global_load_dwordx4 v[222:225], v153, s[16:17] offset:576 nt
	s_mov_b32 s16, s90
	s_mov_b32 s17, s91
	s_waitcnt vmcnt(15)
	v_pk_add_f32 v[148:149], v[126:127], v[148:149]
	v_pk_add_f32 v[150:151], v[128:129], v[150:151]
	global_store_dwordx4 v153, v[148:151], s[16:17]
	s_waitcnt vmcnt(15)
	v_pk_add_f32 v[158:159], v[122:123], v[158:159]
	v_pk_add_f32 v[160:161], v[124:125], v[160:161]
	global_store_dwordx4 v153, v[158:161], s[16:17] offset:64
	s_waitcnt vmcnt(15)
	v_pk_add_f32 v[162:163], v[118:119], v[162:163]
	v_pk_add_f32 v[164:165], v[120:121], v[164:165]
	global_store_dwordx4 v153, v[162:165], s[16:17] offset:512
	s_waitcnt vmcnt(15)
	v_pk_add_f32 v[166:167], v[114:115], v[166:167]
	v_pk_add_f32 v[168:169], v[116:117], v[168:169]
	global_store_dwordx4 v153, v[166:169], s[16:17] offset:576
	s_add_u32 s16, s16, 0x10000
	s_addc_u32 s17, s17, 0
	s_waitcnt vmcnt(15)
	v_pk_add_f32 v[178:179], v[110:111], v[178:179]
	v_pk_add_f32 v[180:181], v[112:113], v[180:181]
	global_store_dwordx4 v153, v[178:181], s[16:17]
	s_waitcnt vmcnt(15)
	v_pk_add_f32 v[182:183], v[106:107], v[182:183]
	v_pk_add_f32 v[184:185], v[108:109], v[184:185]
	global_store_dwordx4 v153, v[182:185], s[16:17] offset:64
	s_waitcnt vmcnt(15)
	v_pk_add_f32 v[186:187], v[102:103], v[186:187]
	v_pk_add_f32 v[188:189], v[104:105], v[188:189]
	global_store_dwordx4 v153, v[186:189], s[16:17] offset:512
	s_waitcnt vmcnt(15)
	v_pk_add_f32 v[190:191], v[98:99], v[190:191]
	v_pk_add_f32 v[192:193], v[100:101], v[192:193]
	global_store_dwordx4 v153, v[190:193], s[16:17] offset:576
	s_add_u32 s16, s16, 0x10000
	s_addc_u32 s17, s17, 0
	s_waitcnt vmcnt(15)
	v_pk_add_f32 v[194:195], v[94:95], v[194:195]
	v_pk_add_f32 v[196:197], v[96:97], v[196:197]
	global_store_dwordx4 v153, v[194:197], s[16:17]
	s_waitcnt vmcnt(15)
	v_pk_add_f32 v[198:199], v[90:91], v[198:199]
	v_pk_add_f32 v[200:201], v[92:93], v[200:201]
	global_store_dwordx4 v153, v[198:201], s[16:17] offset:64
	s_waitcnt vmcnt(15)
	v_pk_add_f32 v[202:203], v[86:87], v[202:203]
	v_pk_add_f32 v[204:205], v[88:89], v[204:205]
	global_store_dwordx4 v153, v[202:205], s[16:17] offset:512
	s_waitcnt vmcnt(15)
	v_pk_add_f32 v[206:207], v[82:83], v[206:207]
	v_pk_add_f32 v[208:209], v[84:85], v[208:209]
	global_store_dwordx4 v153, v[206:209], s[16:17] offset:576
	s_add_u32 s16, s16, 0x10000
	s_addc_u32 s17, s17, 0
	s_waitcnt vmcnt(15)
	v_pk_add_f32 v[210:211], v[78:79], v[210:211]
	v_pk_add_f32 v[212:213], v[80:81], v[212:213]
	global_store_dwordx4 v153, v[210:213], s[16:17]
	s_waitcnt vmcnt(15)
	v_pk_add_f32 v[214:215], v[74:75], v[214:215]
	v_pk_add_f32 v[216:217], v[76:77], v[216:217]
	global_store_dwordx4 v153, v[214:217], s[16:17] offset:64
	s_waitcnt vmcnt(15)
	v_pk_add_f32 v[218:219], v[70:71], v[218:219]
	v_pk_add_f32 v[220:221], v[72:73], v[220:221]
	global_store_dwordx4 v153, v[218:221], s[16:17] offset:512
	s_waitcnt vmcnt(15)
; #define PG8_BAR __builtin_amdgcn_s_barrier()
; template <class Epi>
; DI void gemm_phase(LAS unsigned char* lds, const Gemm g, const Order& S, const Epi& E) {
;     ...
;         if (!has_next) break;
;         if (!keep)
; #pragma unroll
;         for (int a = 0; a < 2; ++a)
; #pragma unroll
;             for (int b = 0; b < 2; ++b)
; #pragma unroll
;                 for (int m = 0; m < 4; ++m)
; #pragma unroll
;                     for (int n = 0; n < 2; ++n) acc[a][b][m][n] = (f32x4){0.f, 0.f, 0.f, 0.f};
;         cur = nxt; cA = nA; cB = nB; ++ui;
;         if (wr == 1) PG8_BAR;
;     DI void operator()(const f32x4 (&acc)[2][2][4][2], const pg8::Unit& u, int wr, int wc, int fr, int fq) const {
;         const int row0 = u.pm * 256 + wr * 64 + fr, col0 = u.pn * 256 + wc * 32 + 4 * fq;
; #pragma unroll
;         for (int ai = 0; ai < 2; ++ai)
; #pragma unroll
;             for (int m = 0; m < 4; ++m) { const size_t off = (size_t)(row0 + ai * 128 + m * 16) * D + col0;
; #pragma unroll
;                 for (int bj = 0; bj < 2; ++bj)
; #pragma unroll
;                     for (int n = 0; n < 2; ++n) { const f32x4 xv = *(const f32x4*)(xin + off + bj * 128 + n * 16); *(f32x4*)(out + off + bj * 128 + n * 16) = xv + acc[ai][bj][m][n]; }
;                 asm volatile("" ::: "memory"); }
;     }
	v_pk_add_f32 v[222:223], v[66:67], v[222:223]
	v_pk_add_f32 v[224:225], v[68:69], v[224:225]
	global_store_dwordx4 v153, v[222:225], s[16:17] offset:576
	s_add_u32 s16, s50, 0x80000
	s_addc_u32 s17, s51, 0
	global_load_dwordx4 v[148:151], v153, s[16:17] nt
	global_load_dwordx4 v[158:161], v153, s[16:17] offset:64 nt
	global_load_dwordx4 v[162:165], v153, s[16:17] offset:512 nt
	global_load_dwordx4 v[166:169], v153, s[16:17] offset:576 nt
	s_add_u32 s16, s16, 0x10000
	s_addc_u32 s17, s17, 0
	global_load_dwordx4 v[178:181], v153, s[16:17] nt
	global_load_dwordx4 v[182:185], v153, s[16:17] offset:64 nt
	global_load_dwordx4 v[186:189], v153, s[16:17] offset:512 nt
	global_load_dwordx4 v[190:193], v153, s[16:17] offset:576 nt
	s_add_u32 s16, s16, 0x10000
	s_addc_u32 s17, s17, 0
	global_load_dwordx4 v[194:197], v153, s[16:17] nt
	global_load_dwordx4 v[198:201], v153, s[16:17] offset:64 nt
	global_load_dwordx4 v[202:205], v153, s[16:17] offset:512 nt
	global_load_dwordx4 v[206:209], v153, s[16:17] offset:576 nt
	s_add_u32 s16, s16, 0x10000
	s_addc_u32 s17, s17, 0
	global_load_dwordx4 v[210:213], v153, s[16:17] nt
	global_load_dwordx4 v[214:217], v153, s[16:17] offset:64 nt
	global_load_dwordx4 v[218:221], v153, s[16:17] offset:512 nt
	global_load_dwordx4 v[222:225], v153, s[16:17] offset:576 nt
	s_add_u32 s16, s90, 0x80000
	s_addc_u32 s17, s91, 0
	s_waitcnt vmcnt(15)
	v_pk_add_f32 v[148:149], v[62:63], v[148:149]
	v_pk_add_f32 v[150:151], v[64:65], v[150:151]
	global_store_dwordx4 v153, v[148:151], s[16:17]
	s_waitcnt vmcnt(15)
	v_pk_add_f32 v[158:159], v[58:59], v[158:159]
	v_pk_add_f32 v[160:161], v[60:61], v[160:161]
	global_store_dwordx4 v153, v[158:161], s[16:17] offset:64
	s_waitcnt vmcnt(15)
	v_pk_add_f32 v[162:163], v[54:55], v[162:163]
	v_pk_add_f32 v[164:165], v[56:57], v[164:165]
	global_store_dwordx4 v153, v[162:165], s[16:17] offset:512
	s_waitcnt vmcnt(15)
	v_pk_add_f32 v[166:167], v[50:51], v[166:167]
	v_pk_add_f32 v[168:169], v[52:53], v[168:169]
	global_store_dwordx4 v153, v[166:169], s[16:17] offset:576
	s_add_u32 s16, s16, 0x10000
	s_addc_u32 s17, s17, 0
	s_waitcnt vmcnt(15)
	v_pk_add_f32 v[178:179], v[44:45], v[178:179]
	v_pk_add_f32 v[180:181], v[46:47], v[180:181]
	global_store_dwordx4 v153, v[178:181], s[16:17]
	s_waitcnt vmcnt(15)
	v_pk_add_f32 v[182:183], v[40:41], v[182:183]
	v_pk_add_f32 v[184:185], v[42:43], v[184:185]
	global_store_dwordx4 v153, v[182:185], s[16:17] offset:64
	s_waitcnt vmcnt(15)
	v_pk_add_f32 v[186:187], v[36:37], v[186:187]
	v_pk_add_f32 v[188:189], v[38:39], v[188:189]
	global_store_dwordx4 v153, v[186:189], s[16:17] offset:512
	s_waitcnt vmcnt(15)
	v_pk_add_f32 v[190:191], v[32:33], v[190:191]
	v_pk_add_f32 v[192:193], v[34:35], v[192:193]
	global_store_dwordx4 v153, v[190:193], s[16:17] offset:576
	s_add_u32 s16, s16, 0x10000
	s_addc_u32 s17, s17, 0
	s_waitcnt vmcnt(15)
	v_pk_add_f32 v[194:195], v[28:29], v[194:195]
	v_pk_add_f32 v[196:197], v[30:31], v[196:197]
	global_store_dwordx4 v153, v[194:197], s[16:17]
	s_waitcnt vmcnt(15)
	v_pk_add_f32 v[198:199], v[24:25], v[198:199]
	v_pk_add_f32 v[200:201], v[26:27], v[200:201]
	global_store_dwordx4 v153, v[198:201], s[16:17] offset:64
	s_waitcnt vmcnt(15)
	v_pk_add_f32 v[202:203], v[20:21], v[202:203]
	v_pk_add_f32 v[204:205], v[22:23], v[204:205]
	global_store_dwordx4 v153, v[202:205], s[16:17] offset:512
	s_waitcnt vmcnt(15)
	v_pk_add_f32 v[206:207], v[16:17], v[206:207]
	v_pk_add_f32 v[208:209], v[18:19], v[208:209]
	global_store_dwordx4 v153, v[206:209], s[16:17] offset:576
	s_add_u32 s16, s16, 0x10000
	s_addc_u32 s17, s17, 0
	s_waitcnt vmcnt(15)
	v_pk_add_f32 v[210:211], v[12:13], v[210:211]
	v_pk_add_f32 v[212:213], v[14:15], v[212:213]
	global_store_dwordx4 v153, v[210:213], s[16:17]
	s_waitcnt vmcnt(15)
	v_pk_add_f32 v[214:215], v[8:9], v[214:215]
	v_pk_add_f32 v[216:217], v[10:11], v[216:217]
	global_store_dwordx4 v153, v[214:217], s[16:17] offset:64
	s_waitcnt vmcnt(15)
	v_pk_add_f32 v[218:219], v[4:5], v[218:219]
	v_pk_add_f32 v[220:221], v[6:7], v[220:221]
	global_store_dwordx4 v153, v[218:221], s[16:17] offset:512
	s_waitcnt vmcnt(15)
	v_pk_add_f32 v[222:223], v[0:1], v[222:223]
	v_pk_add_f32 v[224:225], v[2:3], v[224:225]
	global_store_dwordx4 v153, v[222:225], s[16:17] offset:576
	s_mov_b64 s[16:17], -1
	s_cbranch_vccnz .LBB0_212
	s_andn2_b64 vcc, exec, s[0:1]
	s_cbranch_vccnz .LBB0_211
	s_barrier
	s_branch .LBB0_211
